# FFN-in load balance in the last layer only: 5 full units + one half-row unit per workgroup
# speedup vs baseline: 1.0165x; 1.0165x over previous
.LBB0_661:
	s_add_i32 s79, s79, 1
	s_mul_i32 s6, s79, s78
	s_mul_hi_u32 s10, s79, s4
	s_add_i32 s10, s10, s6
	s_mul_i32 s6, s79, s4
	s_add_u32 s62, s6, s5
	s_addc_u32 s63, s10, s8
	s_movk_i32 s6, 0x580
	s_cmp_lg_u32 s94, 0
	s_cselect_b32 s6, 0x600, s6
	v_mov_b32_e32 v4, s6
	v_mov_b32_e32 v5, 0
	v_cmp_lt_i64_e64 s[12:13], s[62:63], v[4:5]
	s_add_i32 s6, s6, -1
	v_mov_b32_e32 v4, s6
	v_cmp_gt_i64_e32 vcc, s[62:63], v[4:5]
	s_cbranch_vccnz .LBB0_663
	s_mov_b32 s60, s66
	s_add_i32 s58, s14, 4
	s_cmp_lg_u32 s94, 0
	s_cbranch_scc0 .Lh4_nomap
	s_cmp_eq_u32 s79, 5
	s_cbranch_scc0 .Lh4_nomap
	s_sub_i32 s58, s58, 20
	s_and_b32 s99, s58, 1
	s_lshr_b32 s58, s58, 1
	s_add_i32 s58, s58, 20
.Lh4_nomap:
.LBB0_663:
	s_ashr_i32 s61, s60, 31
	s_lshl_b64 s[10:11], s[60:61], 19
	s_add_u32 s62, s21, s10
	s_addc_u32 s63, s24, s11
	s_and_b64 s[10:11], s[12:13], exec
	s_cselect_b32 s10, s63, s69
	s_cselect_b32 s11, s62, s68
	s_ashr_i32 s59, s58, 31
	s_lshl_b64 s[64:65], s[58:59], 19
	s_add_u32 s64, s27, s64
	s_addc_u32 s65, s34, s65
	s_and_b64 s[72:73], s[12:13], exec
	s_cselect_b32 s15, s65, s71
	s_cselect_b32 s59, s64, s70
	s_add_u32 s68, s68, 0x40080
	s_addc_u32 s69, s69, 0
	s_add_u32 s61, s70, 0x100
	s_addc_u32 s67, s71, 0
	s_mov_b32 s80, -2
	s_cmp_lg_u32 s94, 0
	s_cbranch_scc0 .Lh4_full
	s_cmp_eq_u32 s79, 6
	s_cbranch_scc1 .Lh4_unit
.Lh4_full:
	s_add_u32 s6, s68, 0xfffc0080
	s_addc_u32 s33, s69, -1
	s_add_i32 s82, 0, 0x10000
	s_cmp_eq_u32 s80, 12
	s_cselect_b32 s73, s10, s33
	s_cselect_b32 s72, s11, s6
	v_add_u32_e32 v2, s82, v148
	s_cselect_b32 s71, s15, s67
	s_cselect_b32 s70, s59, s61
	s_add_i32 s6, 0, 0x14000
	ds_read_b128 v[152:155], v2
	ds_read_b128 v[156:159], v2 offset:1024
	ds_read_b128 v[160:163], v2 offset:2048
	ds_read_b128 v[168:171], v2 offset:3072
	v_add_u32_e32 v2, s6, v148
	ds_read_b128 v[174:177], v2
	ds_read_b128 v[178:181], v2 offset:1024
	ds_read_b128 v[182:185], v2 offset:2048
	ds_read_b128 v[186:189], v2 offset:3072
	v_lshl_add_u64 v[146:147], s[68:69], 0, v[142:143]
	s_add_i32 m0, s35, 0xc000
	ds_read_b128 v[200:203], v151
	ds_read_b128 v[204:207], v151 offset:1024
	ds_read_b128 v[208:211], v151 offset:2048
	ds_read_b128 v[212:215], v151 offset:3072
	ds_read_b128 v[216:219], v151 offset:4096
	ds_read_b128 v[220:223], v151 offset:5120
	ds_read_b128 v[224:227], v151 offset:6144
	ds_read_b128 v[228:231], v151 offset:7168
	global_load_lds_dwordx4 v[146:147], off
	v_lshl_add_u64 v[146:147], s[68:69], 0, v[144:145]
	s_add_i32 m0, s35, 0xe000
	s_nop 0
	global_load_lds_dwordx4 v[146:147], off
	s_waitcnt vmcnt(8)
	s_waitcnt lgkmcnt(0)
	s_barrier
	s_waitcnt lgkmcnt(0)
	v_mfma_f32_16x16x32_bf16 v[128:131], v[152:155], v[200:203], 0
	v_mfma_f32_16x16x32_bf16 v[120:123], v[160:163], v[200:203], 0
	v_mfma_f32_16x16x32_bf16 v[112:115], v[152:155], v[208:211], 0
	v_mfma_f32_16x16x32_bf16 v[104:107], v[160:163], v[208:211], 0
	v_mfma_f32_16x16x32_bf16 v[96:99], v[152:155], v[216:219], 0
	v_mfma_f32_16x16x32_bf16 v[88:91], v[160:163], v[216:219], 0
	v_mfma_f32_16x16x32_bf16 v[80:83], v[152:155], v[224:227], 0
	v_mfma_f32_16x16x32_bf16 v[72:75], v[160:163], v[224:227], 0
	v_mfma_f32_16x16x32_bf16 v[128:131], v[156:159], v[204:207], v[128:131]
	v_mfma_f32_16x16x32_bf16 v[120:123], v[168:171], v[204:207], v[120:123]
	v_mfma_f32_16x16x32_bf16 v[112:115], v[156:159], v[212:215], v[112:115]
	v_mfma_f32_16x16x32_bf16 v[104:107], v[168:171], v[212:215], v[104:107]
	v_mfma_f32_16x16x32_bf16 v[96:99], v[156:159], v[220:223], v[96:99]
	v_mfma_f32_16x16x32_bf16 v[88:91], v[168:171], v[220:223], v[88:91]
	v_mfma_f32_16x16x32_bf16 v[80:83], v[156:159], v[228:231], v[80:83]
	v_mfma_f32_16x16x32_bf16 v[72:75], v[168:171], v[228:231], v[72:75]
	v_mfma_f32_16x16x32_bf16 v[124:127], v[174:177], v[200:203], 0
	v_mfma_f32_16x16x32_bf16 v[116:119], v[182:185], v[200:203], 0
	v_mfma_f32_16x16x32_bf16 v[108:111], v[174:177], v[208:211], 0
	v_mfma_f32_16x16x32_bf16 v[100:103], v[182:185], v[208:211], 0
	v_mfma_f32_16x16x32_bf16 v[92:95], v[174:177], v[216:219], 0
	v_mfma_f32_16x16x32_bf16 v[84:87], v[182:185], v[216:219], 0
	v_mfma_f32_16x16x32_bf16 v[76:79], v[174:177], v[224:227], 0
	v_mfma_f32_16x16x32_bf16 v[68:71], v[182:185], v[224:227], 0
	v_mfma_f32_16x16x32_bf16 v[124:127], v[178:181], v[204:207], v[124:127]
	v_mfma_f32_16x16x32_bf16 v[116:119], v[186:189], v[204:207], v[116:119]
	v_mfma_f32_16x16x32_bf16 v[108:111], v[178:181], v[212:215], v[108:111]
	v_mfma_f32_16x16x32_bf16 v[100:103], v[186:189], v[212:215], v[100:103]
	v_mfma_f32_16x16x32_bf16 v[92:95], v[178:181], v[220:223], v[92:95]
	v_mfma_f32_16x16x32_bf16 v[84:87], v[186:189], v[220:223], v[84:87]
	v_mfma_f32_16x16x32_bf16 v[76:79], v[178:181], v[228:231], v[76:79]
	v_mfma_f32_16x16x32_bf16 v[68:71], v[186:189], v[228:231], v[68:71]
	s_barrier
	s_add_i32 s33, s82, s20
	v_lshl_add_u64 v[146:147], s[70:71], 0, v[134:135]
	s_mov_b32 m0, s33
	ds_read_b128 v[200:203], v151 offset:16384
	ds_read_b128 v[204:207], v151 offset:17408
	ds_read_b128 v[208:211], v151 offset:18432
	ds_read_b128 v[212:215], v151 offset:19456
	ds_read_b128 v[216:219], v151 offset:20480
	ds_read_b128 v[220:223], v151 offset:21504
	ds_read_b128 v[224:227], v151 offset:22528
	ds_read_b128 v[228:231], v151 offset:23552
	global_load_lds_dwordx4 v[146:147], off
	s_add_i32 m0, s33, 0x2000
	s_add_u32 s82, s70, 0x40000
	v_lshl_add_u64 v[164:165], s[70:71], 0, v[138:139]
	s_addc_u32 s83, s71, 0
	s_add_i32 s6, s6, s20
	global_load_lds_dwordx4 v[164:165], off
	v_lshl_add_u64 v[232:233], s[82:83], 0, v[134:135]
	s_mov_b32 m0, s6
	v_lshl_add_u64 v[234:235], s[72:73], 0, v[136:137]
	global_load_lds_dwordx4 v[232:233], off
	v_lshl_add_u64 v[232:233], s[82:83], 0, v[138:139]
	s_add_i32 m0, s6, 0x2000
	s_nop 0
	global_load_lds_dwordx4 v[232:233], off
	v_lshl_add_u64 v[232:233], s[72:73], 0, v[132:133]
	s_mov_b32 m0, s35
	s_nop 0
	global_load_lds_dwordx4 v[232:233], off
	s_mov_b32 m0, s54
	s_nop 0
	global_load_lds_dwordx4 v[234:235], off
	s_waitcnt vmcnt(8)
	s_waitcnt lgkmcnt(0)
	s_barrier
	s_waitcnt lgkmcnt(0)
	v_mfma_f32_16x16x32_bf16 v[64:67], v[152:155], v[200:203], 0
	v_mfma_f32_16x16x32_bf16 v[56:59], v[160:163], v[200:203], 0
	v_mfma_f32_16x16x32_bf16 v[48:51], v[152:155], v[208:211], 0
	v_mfma_f32_16x16x32_bf16 v[40:43], v[160:163], v[208:211], 0
	v_mfma_f32_16x16x32_bf16 v[32:35], v[152:155], v[216:219], 0
	v_mfma_f32_16x16x32_bf16 v[24:27], v[160:163], v[216:219], 0
	v_mfma_f32_16x16x32_bf16 v[16:19], v[152:155], v[224:227], 0
	v_mfma_f32_16x16x32_bf16 v[8:11], v[160:163], v[224:227], 0
	v_mfma_f32_16x16x32_bf16 v[64:67], v[156:159], v[204:207], v[64:67]
	v_mfma_f32_16x16x32_bf16 v[56:59], v[168:171], v[204:207], v[56:59]
	v_mfma_f32_16x16x32_bf16 v[48:51], v[156:159], v[212:215], v[48:51]
	v_mfma_f32_16x16x32_bf16 v[40:43], v[168:171], v[212:215], v[40:43]
	v_mfma_f32_16x16x32_bf16 v[32:35], v[156:159], v[220:223], v[32:35]
	v_mfma_f32_16x16x32_bf16 v[24:27], v[168:171], v[220:223], v[24:27]
	v_mfma_f32_16x16x32_bf16 v[16:19], v[156:159], v[228:231], v[16:19]
	v_mfma_f32_16x16x32_bf16 v[8:11], v[168:171], v[228:231], v[8:11]
	v_mfma_f32_16x16x32_bf16 v[60:63], v[174:177], v[200:203], 0
	v_mfma_f32_16x16x32_bf16 v[52:55], v[182:185], v[200:203], 0
	v_mfma_f32_16x16x32_bf16 v[44:47], v[174:177], v[208:211], 0
	v_mfma_f32_16x16x32_bf16 v[36:39], v[182:185], v[208:211], 0
	v_mfma_f32_16x16x32_bf16 v[28:31], v[174:177], v[216:219], 0
	v_mfma_f32_16x16x32_bf16 v[20:23], v[182:185], v[216:219], 0
	v_mfma_f32_16x16x32_bf16 v[12:15], v[174:177], v[224:227], 0
	v_mfma_f32_16x16x32_bf16 v[4:7], v[182:185], v[224:227], 0
	v_mfma_f32_16x16x32_bf16 v[60:63], v[178:181], v[204:207], v[60:63]
	v_mfma_f32_16x16x32_bf16 v[52:55], v[186:189], v[204:207], v[52:55]
	v_mfma_f32_16x16x32_bf16 v[44:47], v[178:181], v[212:215], v[44:47]
	v_mfma_f32_16x16x32_bf16 v[36:39], v[186:189], v[212:215], v[36:39]
	v_mfma_f32_16x16x32_bf16 v[28:31], v[178:181], v[220:223], v[28:31]
	v_mfma_f32_16x16x32_bf16 v[20:23], v[186:189], v[220:223], v[20:23]
	v_mfma_f32_16x16x32_bf16 v[12:15], v[178:181], v[228:231], v[12:15]
	v_mfma_f32_16x16x32_bf16 v[4:7], v[186:189], v[228:231], v[4:7]
	s_barrier
	s_add_i32 s6, 0, 0x18000
	v_add_u32_e32 v2, s6, v148
	s_add_i32 s33, 0, 0x1c000
	ds_read_b128 v[152:155], v2
	ds_read_b128 v[156:159], v2 offset:1024
	ds_read_b128 v[160:163], v2 offset:2048
	ds_read_b128 v[168:171], v2 offset:3072
	v_add_u32_e32 v2, s33, v148
	ds_read_b128 v[174:177], v2
	ds_read_b128 v[178:181], v2 offset:1024
	ds_read_b128 v[182:185], v2 offset:2048
	ds_read_b128 v[186:189], v2 offset:3072
	s_add_u32 s72, s72, 0x40000
	s_addc_u32 s73, s73, 0
	s_mov_b32 m0, s55
	v_lshl_add_u64 v[236:237], s[72:73], 0, v[132:133]
	ds_read_b128 v[200:203], v151 offset:32768
	ds_read_b128 v[204:207], v151 offset:33792
	ds_read_b128 v[208:211], v151 offset:34816
	ds_read_b128 v[212:215], v151 offset:35840
	ds_read_b128 v[216:219], v151 offset:36864
	ds_read_b128 v[220:223], v151 offset:37888
	ds_read_b128 v[224:227], v151 offset:38912
	ds_read_b128 v[228:231], v151 offset:39936
	global_load_lds_dwordx4 v[236:237], off
	v_lshl_add_u64 v[236:237], s[72:73], 0, v[136:137]
	s_mov_b32 m0, s56
	s_nop 0
	global_load_lds_dwordx4 v[236:237], off
	s_waitcnt vmcnt(8)
	s_waitcnt lgkmcnt(0)
	s_barrier
	s_waitcnt lgkmcnt(0)
	v_mfma_f32_16x16x32_bf16 v[128:131], v[152:155], v[200:203], v[128:131]
	v_mfma_f32_16x16x32_bf16 v[120:123], v[160:163], v[200:203], v[120:123]
	v_mfma_f32_16x16x32_bf16 v[112:115], v[152:155], v[208:211], v[112:115]
	v_mfma_f32_16x16x32_bf16 v[104:107], v[160:163], v[208:211], v[104:107]
	v_mfma_f32_16x16x32_bf16 v[96:99], v[152:155], v[216:219], v[96:99]
	v_mfma_f32_16x16x32_bf16 v[88:91], v[160:163], v[216:219], v[88:91]
	v_mfma_f32_16x16x32_bf16 v[80:83], v[152:155], v[224:227], v[80:83]
	v_mfma_f32_16x16x32_bf16 v[72:75], v[160:163], v[224:227], v[72:75]
	v_mfma_f32_16x16x32_bf16 v[128:131], v[156:159], v[204:207], v[128:131]
	v_mfma_f32_16x16x32_bf16 v[120:123], v[168:171], v[204:207], v[120:123]
	v_mfma_f32_16x16x32_bf16 v[112:115], v[156:159], v[212:215], v[112:115]
	v_mfma_f32_16x16x32_bf16 v[104:107], v[168:171], v[212:215], v[104:107]
	v_mfma_f32_16x16x32_bf16 v[96:99], v[156:159], v[220:223], v[96:99]
	v_mfma_f32_16x16x32_bf16 v[88:91], v[168:171], v[220:223], v[88:91]
	v_mfma_f32_16x16x32_bf16 v[80:83], v[156:159], v[228:231], v[80:83]
	v_mfma_f32_16x16x32_bf16 v[72:75], v[168:171], v[228:231], v[72:75]
	v_mfma_f32_16x16x32_bf16 v[124:127], v[174:177], v[200:203], v[124:127]
	v_mfma_f32_16x16x32_bf16 v[116:119], v[182:185], v[200:203], v[116:119]
	v_mfma_f32_16x16x32_bf16 v[108:111], v[174:177], v[208:211], v[108:111]
	v_mfma_f32_16x16x32_bf16 v[100:103], v[182:185], v[208:211], v[100:103]
	v_mfma_f32_16x16x32_bf16 v[92:95], v[174:177], v[216:219], v[92:95]
	v_mfma_f32_16x16x32_bf16 v[84:87], v[182:185], v[216:219], v[84:87]
	v_mfma_f32_16x16x32_bf16 v[76:79], v[174:177], v[224:227], v[76:79]
	v_mfma_f32_16x16x32_bf16 v[68:71], v[182:185], v[224:227], v[68:71]
	v_mfma_f32_16x16x32_bf16 v[124:127], v[178:181], v[204:207], v[124:127]
	v_mfma_f32_16x16x32_bf16 v[116:119], v[186:189], v[204:207], v[116:119]
	v_mfma_f32_16x16x32_bf16 v[108:111], v[178:181], v[212:215], v[108:111]
	v_mfma_f32_16x16x32_bf16 v[100:103], v[186:189], v[212:215], v[100:103]
	v_mfma_f32_16x16x32_bf16 v[92:95], v[178:181], v[220:223], v[92:95]
	v_mfma_f32_16x16x32_bf16 v[84:87], v[186:189], v[220:223], v[84:87]
	v_mfma_f32_16x16x32_bf16 v[76:79], v[178:181], v[228:231], v[76:79]
	v_mfma_f32_16x16x32_bf16 v[68:71], v[186:189], v[228:231], v[68:71]
	s_barrier
	s_add_i32 s6, s6, s20
	v_lshl_add_u64 v[146:147], v[146:147], 0, s[30:31]
	s_mov_b32 m0, s6
	ds_read_b128 v[200:203], v151 offset:49152
	ds_read_b128 v[204:207], v151 offset:50176
	ds_read_b128 v[208:211], v151 offset:51200
	ds_read_b128 v[212:215], v151 offset:52224
	ds_read_b128 v[216:219], v151 offset:53248
	ds_read_b128 v[220:223], v151 offset:54272
	ds_read_b128 v[224:227], v151 offset:55296
	ds_read_b128 v[228:231], v151 offset:56320
	global_load_lds_dwordx4 v[146:147], off
	s_add_i32 m0, s6, 0x2000
	s_add_u32 s70, s70, 0x40080
	v_lshl_add_u64 v[146:147], v[164:165], 0, s[30:31]
	s_addc_u32 s71, s71, 0
	s_add_i32 s6, s33, s20
	global_load_lds_dwordx4 v[146:147], off
	v_lshl_add_u64 v[146:147], s[70:71], 0, v[134:135]
	s_mov_b32 m0, s6
	s_nop 0
	global_load_lds_dwordx4 v[146:147], off
	v_lshl_add_u64 v[146:147], s[70:71], 0, v[138:139]
	s_add_i32 m0, s6, 0x2000
	s_nop 0
	global_load_lds_dwordx4 v[146:147], off
	v_lshl_add_u64 v[146:147], v[232:233], 0, s[30:31]
	s_mov_b32 m0, s76
	s_nop 0
	global_load_lds_dwordx4 v[146:147], off
	v_lshl_add_u64 v[146:147], v[234:235], 0, s[30:31]
	s_mov_b32 m0, s77
	s_nop 0
	global_load_lds_dwordx4 v[146:147], off
	s_waitcnt vmcnt(8)
	s_waitcnt lgkmcnt(0)
	s_barrier
	s_waitcnt lgkmcnt(0)
	v_mfma_f32_16x16x32_bf16 v[64:67], v[152:155], v[200:203], v[64:67]
	v_mfma_f32_16x16x32_bf16 v[56:59], v[160:163], v[200:203], v[56:59]
	v_mfma_f32_16x16x32_bf16 v[48:51], v[152:155], v[208:211], v[48:51]
	v_mfma_f32_16x16x32_bf16 v[40:43], v[160:163], v[208:211], v[40:43]
	v_mfma_f32_16x16x32_bf16 v[32:35], v[152:155], v[216:219], v[32:35]
	v_mfma_f32_16x16x32_bf16 v[24:27], v[160:163], v[216:219], v[24:27]
	v_mfma_f32_16x16x32_bf16 v[16:19], v[152:155], v[224:227], v[16:19]
	v_mfma_f32_16x16x32_bf16 v[8:11], v[160:163], v[224:227], v[8:11]
	v_mfma_f32_16x16x32_bf16 v[64:67], v[156:159], v[204:207], v[64:67]
	v_mfma_f32_16x16x32_bf16 v[56:59], v[168:171], v[204:207], v[56:59]
	v_mfma_f32_16x16x32_bf16 v[48:51], v[156:159], v[212:215], v[48:51]
	v_mfma_f32_16x16x32_bf16 v[40:43], v[168:171], v[212:215], v[40:43]
	v_mfma_f32_16x16x32_bf16 v[32:35], v[156:159], v[220:223], v[32:35]
	v_mfma_f32_16x16x32_bf16 v[24:27], v[168:171], v[220:223], v[24:27]
	v_mfma_f32_16x16x32_bf16 v[16:19], v[156:159], v[228:231], v[16:19]
	v_mfma_f32_16x16x32_bf16 v[8:11], v[168:171], v[228:231], v[8:11]
	v_mfma_f32_16x16x32_bf16 v[60:63], v[174:177], v[200:203], v[60:63]
	v_mfma_f32_16x16x32_bf16 v[52:55], v[182:185], v[200:203], v[52:55]
	v_mfma_f32_16x16x32_bf16 v[44:47], v[174:177], v[208:211], v[44:47]
	v_mfma_f32_16x16x32_bf16 v[36:39], v[182:185], v[208:211], v[36:39]
	v_mfma_f32_16x16x32_bf16 v[28:31], v[174:177], v[216:219], v[28:31]
	v_mfma_f32_16x16x32_bf16 v[20:23], v[182:185], v[216:219], v[20:23]
	v_mfma_f32_16x16x32_bf16 v[12:15], v[174:177], v[224:227], v[12:15]
	v_mfma_f32_16x16x32_bf16 v[4:7], v[182:185], v[224:227], v[4:7]
	v_mfma_f32_16x16x32_bf16 v[60:63], v[178:181], v[204:207], v[60:63]
	v_mfma_f32_16x16x32_bf16 v[52:55], v[186:189], v[204:207], v[52:55]
	v_mfma_f32_16x16x32_bf16 v[44:47], v[178:181], v[212:215], v[44:47]
	v_mfma_f32_16x16x32_bf16 v[36:39], v[186:189], v[212:215], v[36:39]
	v_mfma_f32_16x16x32_bf16 v[28:31], v[178:181], v[220:223], v[28:31]
	v_mfma_f32_16x16x32_bf16 v[20:23], v[186:189], v[220:223], v[20:23]
	v_mfma_f32_16x16x32_bf16 v[12:15], v[178:181], v[228:231], v[12:15]
	v_mfma_f32_16x16x32_bf16 v[4:7], v[186:189], v[228:231], v[4:7]
	s_barrier
	s_add_i32 s80, s80, 2
	s_add_u32 s68, s68, 0x100
	s_addc_u32 s69, s69, 0
	s_add_u32 s61, s61, 0x100
	s_addc_u32 s67, s67, 0
